# P5 rewritten with the same generator (gamma/beta hoisted, next row's loads issued before this row's stores, X/T roles swap per row) on top of the pipelined fused P9
# speedup vs baseline: 1.0118x; 1.0071x over previous
; #define PHASE_IDS() int tid_p = threadIdx.x; asm volatile("" : "+v"(tid_p)); const int lane = tid_p & 63; const int wave_p = __builtin_amdgcn_readfirstlane(tid_p >> 6); \
;     const int gw = vcu * NWAVES + wave_p, NGW = G * NWAVES; const size_t gt = (size_t)bx * NTHREADS + tid_p, NGT = (size_t)G * NTHREADS; (void)lane; (void)gw; (void)NGW; (void)gt; (void)NGT
; __global__ void __launch_bounds__(NTHREADS, 2) fwd_megakernel(Args args) {
;     ...
;     { PHASE_IDS();
;     for (int m = gw; m < MTOK; m += NGW) {
;         float* row = HF + (size_t)m * DM; const float* xr = x + (size_t)m * DM; const bf16* mr = MIXB + (size_t)m * DM; f32x4 v[8]; float s = 0.f;
; #pragma unroll
;         for (int j = 0; j < 8; ++j) { const int c = 4 * (lane + 64 * j); const f32x4 xv = __builtin_nontemporal_load((const f32x4*)(xr + c)); const v2u mv = *(const v2u*)(mr + c);
;             v[j] = xv * ALPHA + (f32x4){bflo(mv.x), bfhi(mv.x), bflo(mv.y), bfhi(mv.y)}; s += (v[j][0] + v[j][1]) + (v[j][2] + v[j][3]); }
;         const float mean = wave_sum(s) * (1.f / DM); float s2 = 0.f;
.LBB0_340:
	s_or_b64 exec, exec, s[4:5]
	s_waitcnt lgkmcnt(0)
	v_mov_b32_e32 v0, v178
	s_barrier
	v_writelane_b32 v244, s12, 16
	v_writelane_b32 v244, s13, 17
	v_writelane_b32 v244, s20, 18
	v_writelane_b32 v244, s21, 19
	v_writelane_b32 v244, s22, 20
	v_writelane_b32 v244, s23, 21
	v_mbcnt_lo_u32_b32 v179, -1, 0
	v_readfirstlane_b32 s0, v0
	s_ashr_i32 s4, s0, 6
	s_add_i32 s0, s4, s89
	s_cmpk_gt_i32 s0, 0x7fff
	s_cbranch_scc1 .LBB0_343
	v_mbcnt_lo_u32_b32 v97, -1, 0
	v_mbcnt_hi_u32_b32 v97, -1, v97
	v_lshlrev_b32_e32 v106, 4, v97
	v_add_u32_e32 v107, 0x1000, v106
	v_lshlrev_b32_e32 v108, 3, v97
	v_xor_b32_e32 v109, 1, v97
	v_lshlrev_b32_e32 v109, 2, v109
	v_xor_b32_e32 v110, 2, v97
	v_lshlrev_b32_e32 v110, 2, v110
	v_xor_b32_e32 v111, 4, v97
	v_lshlrev_b32_e32 v111, 2, v111
	v_xor_b32_e32 v240, 8, v97
	v_lshlrev_b32_e32 v240, 2, v240
	v_xor_b32_e32 v241, 16, v97
	v_lshlrev_b32_e32 v241, 2, v241
	v_xor_b32_e32 v242, 32, v97
	v_lshlrev_b32_e32 v242, 2, v242
	v_mov_b32_e32 v105, 0x3727c5ac
	v_mov_b32_e32 v104, 0x260
	global_load_dwordx4 v[112:115], v106, s[20:21]
	global_load_dwordx4 v[116:119], v106, s[20:21] offset:1024
	global_load_dwordx4 v[120:123], v106, s[20:21] offset:2048
	global_load_dwordx4 v[124:127], v106, s[20:21] offset:3072
	global_load_dwordx4 v[128:131], v107, s[20:21]
	global_load_dwordx4 v[132:135], v107, s[20:21] offset:1024
	global_load_dwordx4 v[136:139], v107, s[20:21] offset:2048
	global_load_dwordx4 v[140:143], v107, s[20:21] offset:3072
	global_load_dwordx4 v[144:147], v106, s[22:23]
	global_load_dwordx4 v[148:151], v106, s[22:23] offset:1024
	global_load_dwordx4 v[152:155], v106, s[22:23] offset:2048
	global_load_dwordx4 v[156:159], v106, s[22:23] offset:3072
	global_load_dwordx4 v[160:163], v107, s[22:23]
	global_load_dwordx4 v[164:167], v107, s[22:23] offset:1024
	global_load_dwordx4 v[168:171], v107, s[22:23] offset:2048
	global_load_dwordx4 v[172:175], v107, s[22:23] offset:3072
	s_mov_b32 s10, 0x3f9837f0
	s_mov_b32 s1, 0xf800000
	s_lshl_b32 s4, s0, 13
	s_add_u32 s4, s12, s4
	s_addc_u32 s5, s13, 0
	s_lshl_b32 s8, s0, 12
	s_add_u32 s8, s40, s8
	s_addc_u32 s9, s41, 0
	s_add_u32 s6, s8, 0xfc00000
	s_addc_u32 s7, s9, 0
	s_add_u32 s8, s8, 0x7c00000
	s_addc_u32 s9, s9, 0
	s_lshl_b32 s20, s28, 13
	s_lshl_b32 s21, s28, 12
	global_load_dwordx4 v[0:3], v106, s[4:5] nt
	global_load_dwordx4 v[4:7], v106, s[4:5] offset:1024 nt
	global_load_dwordx4 v[8:11], v106, s[4:5] offset:2048 nt
	global_load_dwordx4 v[12:15], v106, s[4:5] offset:3072 nt
	global_load_dwordx4 v[16:19], v107, s[4:5] nt
	global_load_dwordx4 v[20:23], v107, s[4:5] offset:1024 nt
	global_load_dwordx4 v[24:27], v107, s[4:5] offset:2048 nt
	global_load_dwordx4 v[28:31], v107, s[4:5] offset:3072 nt
	global_load_dwordx2 v[32:33], v108, s[6:7]
	global_load_dwordx2 v[34:35], v108, s[6:7] offset:512
	global_load_dwordx2 v[36:37], v108, s[6:7] offset:1024
	global_load_dwordx2 v[38:39], v108, s[6:7] offset:1536
	global_load_dwordx2 v[40:41], v108, s[6:7] offset:2048
	global_load_dwordx2 v[42:43], v108, s[6:7] offset:2560
	global_load_dwordx2 v[44:45], v108, s[6:7] offset:3072
	global_load_dwordx2 v[46:47], v108, s[6:7] offset:3584
	s_add_u32 s4, s4, s20
	s_addc_u32 s5, s5, 0
	s_add_u32 s6, s6, s21
	s_addc_u32 s7, s7, 0
	s_waitcnt vmcnt(0)
.Lp5r_loop:
	s_waitcnt vmcnt(8)
	v_lshlrev_b32_e32 v64, 16, v32
	v_and_b32_e32 v65, 0xffff0000, v32
	v_lshlrev_b32_e32 v66, 16, v33
	v_and_b32_e32 v67, 0xffff0000, v33
	v_lshlrev_b32_e32 v68, 16, v34
	v_and_b32_e32 v69, 0xffff0000, v34
	v_lshlrev_b32_e32 v70, 16, v35
	v_and_b32_e32 v71, 0xffff0000, v35
	v_lshlrev_b32_e32 v72, 16, v36
	v_and_b32_e32 v73, 0xffff0000, v36
	v_lshlrev_b32_e32 v74, 16, v37
	v_and_b32_e32 v75, 0xffff0000, v37
	v_lshlrev_b32_e32 v76, 16, v38
	v_and_b32_e32 v77, 0xffff0000, v38
	v_lshlrev_b32_e32 v78, 16, v39
	v_and_b32_e32 v79, 0xffff0000, v39
	v_lshlrev_b32_e32 v80, 16, v40
	v_and_b32_e32 v81, 0xffff0000, v40
	v_lshlrev_b32_e32 v82, 16, v41
	v_and_b32_e32 v83, 0xffff0000, v41
	v_lshlrev_b32_e32 v84, 16, v42
	v_and_b32_e32 v85, 0xffff0000, v42
	v_lshlrev_b32_e32 v86, 16, v43
	v_and_b32_e32 v87, 0xffff0000, v43
	v_lshlrev_b32_e32 v88, 16, v44
	v_and_b32_e32 v89, 0xffff0000, v44
	v_lshlrev_b32_e32 v90, 16, v45
	v_and_b32_e32 v91, 0xffff0000, v45
	v_lshlrev_b32_e32 v92, 16, v46
	v_and_b32_e32 v93, 0xffff0000, v46
	v_lshlrev_b32_e32 v94, 16, v47
	v_and_b32_e32 v95, 0xffff0000, v47
	v_pk_fma_f32 v[0:1], v[0:1], s[10:11], v[64:65] op_sel_hi:[1,0,1]
	v_pk_fma_f32 v[2:3], v[2:3], s[10:11], v[66:67] op_sel_hi:[1,0,1]
	v_pk_fma_f32 v[4:5], v[4:5], s[10:11], v[68:69] op_sel_hi:[1,0,1]
	v_pk_fma_f32 v[6:7], v[6:7], s[10:11], v[70:71] op_sel_hi:[1,0,1]
	v_pk_fma_f32 v[8:9], v[8:9], s[10:11], v[72:73] op_sel_hi:[1,0,1]
	v_pk_fma_f32 v[10:11], v[10:11], s[10:11], v[74:75] op_sel_hi:[1,0,1]
	v_pk_fma_f32 v[12:13], v[12:13], s[10:11], v[76:77] op_sel_hi:[1,0,1]
	v_pk_fma_f32 v[14:15], v[14:15], s[10:11], v[78:79] op_sel_hi:[1,0,1]
	v_pk_fma_f32 v[16:17], v[16:17], s[10:11], v[80:81] op_sel_hi:[1,0,1]
	v_pk_fma_f32 v[18:19], v[18:19], s[10:11], v[82:83] op_sel_hi:[1,0,1]
	v_pk_fma_f32 v[20:21], v[20:21], s[10:11], v[84:85] op_sel_hi:[1,0,1]
	v_pk_fma_f32 v[22:23], v[22:23], s[10:11], v[86:87] op_sel_hi:[1,0,1]
	v_pk_fma_f32 v[24:25], v[24:25], s[10:11], v[88:89] op_sel_hi:[1,0,1]
	v_pk_fma_f32 v[26:27], v[26:27], s[10:11], v[90:91] op_sel_hi:[1,0,1]
	v_pk_fma_f32 v[28:29], v[28:29], s[10:11], v[92:93] op_sel_hi:[1,0,1]
	v_pk_fma_f32 v[30:31], v[30:31], s[10:11], v[94:95] op_sel_hi:[1,0,1]
	v_pk_add_f32 v[64:65], v[0:1], v[2:3]
	v_pk_add_f32 v[66:67], v[4:5], v[6:7]
	v_pk_add_f32 v[68:69], v[8:9], v[10:11]
	v_pk_add_f32 v[70:71], v[12:13], v[14:15]
	v_pk_add_f32 v[72:73], v[16:17], v[18:19]
	v_pk_add_f32 v[74:75], v[20:21], v[22:23]
	v_pk_add_f32 v[76:77], v[24:25], v[26:27]
	v_pk_add_f32 v[78:79], v[28:29], v[30:31]
	v_pk_add_f32 v[80:81], v[64:65], v[66:67]
	v_pk_add_f32 v[82:83], v[68:69], v[70:71]
	v_pk_add_f32 v[84:85], v[72:73], v[74:75]
	v_pk_add_f32 v[86:87], v[76:77], v[78:79]
	v_pk_add_f32 v[64:65], v[80:81], v[82:83]
	v_pk_add_f32 v[66:67], v[84:85], v[86:87]
	s_nop 0
	v_pk_add_f32 v[64:65], v[64:65], v[66:67]
	s_nop 0
	v_add_f32_e32 v96, v64, v65
	ds_bpermute_b32 v97, v109, v96
	s_waitcnt lgkmcnt(0)
; __global__ void __launch_bounds__(NTHREADS, 2) fwd_megakernel(Args args) {
;     ...
;         float* row = HF + (size_t)m * DM; const float* xr = x + (size_t)m * DM; const bf16* mr = MIXB + (size_t)m * DM; f32x4 v[8]; float s = 0.f;
; #pragma unroll
;         for (int j = 0; j < 8; ++j) { const int c = 4 * (lane + 64 * j); const f32x4 xv = __builtin_nontemporal_load((const f32x4*)(xr + c)); const v2u mv = *(const v2u*)(mr + c);
;             v[j] = xv * ALPHA + (f32x4){bflo(mv.x), bfhi(mv.x), bflo(mv.y), bfhi(mv.y)}; s += (v[j][0] + v[j][1]) + (v[j][2] + v[j][3]); }
;         const float mean = wave_sum(s) * (1.f / DM); float s2 = 0.f;
; #pragma unroll
;         for (int j = 0; j < 8; ++j) { v[j] = v[j] - mean; s2 += (v[j][0] * v[j][0] + v[j][1] * v[j][1]) + (v[j][2] * v[j][2] + v[j][3] * v[j][3]); }
;         const float rstd = 1.f / sqrtf(wave_sum(s2) * (1.f / DM) + LN_EPS);
; #pragma unroll
;         for (int j = 0; j < 8; ++j) { const int c = 4 * (lane + 64 * j); const f32x4 gg = *(const f32x4*)(ln1_g + c), bb = *(const f32x4*)(ln1_b + c);
;             const f32x4 o = v[j] * rstd * gg + bb; *(f32x4*)(row + c) = o;
	v_add_f32_e32 v96, v96, v97
	ds_bpermute_b32 v97, v110, v96
	s_waitcnt lgkmcnt(0)
	v_add_f32_e32 v96, v96, v97
	ds_bpermute_b32 v97, v111, v96
	s_waitcnt lgkmcnt(0)
	v_add_f32_e32 v96, v96, v97
	ds_bpermute_b32 v97, v240, v96
	s_waitcnt lgkmcnt(0)
	v_add_f32_e32 v96, v96, v97
	ds_bpermute_b32 v97, v241, v96
	s_waitcnt lgkmcnt(0)
	v_add_f32_e32 v96, v96, v97
	ds_bpermute_b32 v97, v242, v96
	s_waitcnt lgkmcnt(0)
	v_add_f32_e32 v96, v96, v97
	v_mul_f32_e32 v96, 0xba000000, v96
	v_pk_add_f32 v[0:1], v[0:1], v[96:97] op_sel_hi:[1,0]
	v_pk_add_f32 v[2:3], v[2:3], v[96:97] op_sel_hi:[1,0]
	v_pk_add_f32 v[4:5], v[4:5], v[96:97] op_sel_hi:[1,0]
	v_pk_add_f32 v[6:7], v[6:7], v[96:97] op_sel_hi:[1,0]
	v_pk_add_f32 v[8:9], v[8:9], v[96:97] op_sel_hi:[1,0]
	v_pk_add_f32 v[10:11], v[10:11], v[96:97] op_sel_hi:[1,0]
	v_pk_add_f32 v[12:13], v[12:13], v[96:97] op_sel_hi:[1,0]
	v_pk_add_f32 v[14:15], v[14:15], v[96:97] op_sel_hi:[1,0]
	v_pk_add_f32 v[16:17], v[16:17], v[96:97] op_sel_hi:[1,0]
	v_pk_add_f32 v[18:19], v[18:19], v[96:97] op_sel_hi:[1,0]
	v_pk_add_f32 v[20:21], v[20:21], v[96:97] op_sel_hi:[1,0]
	v_pk_add_f32 v[22:23], v[22:23], v[96:97] op_sel_hi:[1,0]
	v_pk_add_f32 v[24:25], v[24:25], v[96:97] op_sel_hi:[1,0]
	v_pk_add_f32 v[26:27], v[26:27], v[96:97] op_sel_hi:[1,0]
	v_pk_add_f32 v[28:29], v[28:29], v[96:97] op_sel_hi:[1,0]
	v_pk_add_f32 v[30:31], v[30:31], v[96:97] op_sel_hi:[1,0]
	v_pk_mul_f32 v[64:65], v[0:1], v[0:1]
	v_pk_mul_f32 v[66:67], v[4:5], v[4:5]
	v_pk_mul_f32 v[68:69], v[8:9], v[8:9]
	v_pk_mul_f32 v[70:71], v[12:13], v[12:13]
	v_pk_fma_f32 v[64:65], v[2:3], v[2:3], v[64:65]
	v_pk_fma_f32 v[66:67], v[6:7], v[6:7], v[66:67]
	v_pk_fma_f32 v[68:69], v[10:11], v[10:11], v[68:69]
	v_pk_fma_f32 v[70:71], v[14:15], v[14:15], v[70:71]
	v_pk_fma_f32 v[64:65], v[16:17], v[16:17], v[64:65]
	v_pk_fma_f32 v[66:67], v[20:21], v[20:21], v[66:67]
	v_pk_fma_f32 v[68:69], v[24:25], v[24:25], v[68:69]
	v_pk_fma_f32 v[70:71], v[28:29], v[28:29], v[70:71]
	v_pk_fma_f32 v[64:65], v[18:19], v[18:19], v[64:65]
	v_pk_fma_f32 v[66:67], v[22:23], v[22:23], v[66:67]
	v_pk_fma_f32 v[68:69], v[26:27], v[26:27], v[68:69]
	v_pk_fma_f32 v[70:71], v[30:31], v[30:31], v[70:71]
	v_pk_add_f32 v[64:65], v[64:65], v[66:67]
	v_pk_add_f32 v[68:69], v[68:69], v[70:71]
	s_nop 0
	v_pk_add_f32 v[64:65], v[64:65], v[68:69]
	s_nop 0
	v_add_f32_e32 v96, v64, v65
	ds_bpermute_b32 v97, v109, v96
	s_waitcnt lgkmcnt(0)
	v_add_f32_e32 v96, v96, v97
	ds_bpermute_b32 v97, v110, v96
	s_waitcnt lgkmcnt(0)
	v_add_f32_e32 v96, v96, v97
	ds_bpermute_b32 v97, v111, v96
	s_waitcnt lgkmcnt(0)
	v_add_f32_e32 v96, v96, v97
	ds_bpermute_b32 v97, v240, v96
	s_waitcnt lgkmcnt(0)
	v_add_f32_e32 v96, v96, v97
	ds_bpermute_b32 v97, v241, v96
	s_waitcnt lgkmcnt(0)
	v_add_f32_e32 v96, v96, v97
	ds_bpermute_b32 v97, v242, v96
	s_waitcnt lgkmcnt(0)
	v_add_f32_e32 v96, v96, v97
	v_fmamk_f32 v98, v96, 0x3a000000, v105
	v_mul_f32_e32 v99, 0x4f800000, v98
	v_cmp_gt_f32_e32 vcc, s1, v98
	s_nop 1
	v_cndmask_b32_e32 v98, v98, v99, vcc
	v_sqrt_f32_e32 v99, v98
	s_nop 0
	v_add_u32_e32 v100, -1, v99
	v_add_u32_e32 v101, 1, v99
	v_fma_f32 v102, -v100, v99, v98
	v_fma_f32 v103, -v101, v99, v98
	v_cmp_ge_f32_e64 s[22:23], 0, v102
	s_nop 1
	v_cndmask_b32_e64 v99, v99, v100, s[22:23]
	v_cmp_lt_f32_e64 s[22:23], 0, v103
	s_nop 1
	v_cndmask_b32_e64 v99, v99, v101, s[22:23]
	v_mul_f32_e32 v100, 0x37800000, v99
	v_cndmask_b32_e32 v99, v99, v100, vcc
	v_cmp_class_f32_e32 vcc, v98, v104
	s_nop 1
	v_cndmask_b32_e32 v98, v99, v98, vcc
	v_div_scale_f32 v99, s[22:23], v98, v98, 1.0
	v_rcp_f32_e32 v101, v99
	v_div_scale_f32 v100, vcc, 1.0, v98, 1.0
	v_fma_f32 v102, -v99, v101, 1.0
	v_fmac_f32_e32 v101, v102, v101
	v_mul_f32_e32 v102, v100, v101
	v_fma_f32 v103, -v99, v102, v100
	v_fmac_f32_e32 v102, v103, v101
	v_fma_f32 v99, -v99, v102, v100
	v_div_fmas_f32 v99, v99, v101, v102
	v_div_fixup_f32 v98, v99, v98, 1.0
	s_add_i32 s0, s0, s28
	global_load_dwordx4 v[64:67], v106, s[4:5] nt
	global_load_dwordx4 v[68:71], v106, s[4:5] offset:1024 nt
	global_load_dwordx4 v[72:75], v106, s[4:5] offset:2048 nt
	global_load_dwordx4 v[76:79], v106, s[4:5] offset:3072 nt
	global_load_dwordx4 v[80:83], v107, s[4:5] nt
	global_load_dwordx4 v[84:87], v107, s[4:5] offset:1024 nt
	global_load_dwordx4 v[88:91], v107, s[4:5] offset:2048 nt
	global_load_dwordx4 v[92:95], v107, s[4:5] offset:3072 nt
	global_load_dwordx2 v[32:33], v108, s[6:7]
	global_load_dwordx2 v[34:35], v108, s[6:7] offset:512
	global_load_dwordx2 v[36:37], v108, s[6:7] offset:1024
	global_load_dwordx2 v[38:39], v108, s[6:7] offset:1536
	global_load_dwordx2 v[40:41], v108, s[6:7] offset:2048
	global_load_dwordx2 v[42:43], v108, s[6:7] offset:2560
	global_load_dwordx2 v[44:45], v108, s[6:7] offset:3072
	global_load_dwordx2 v[46:47], v108, s[6:7] offset:3584
	s_add_u32 s4, s4, s20
	s_addc_u32 s5, s5, 0
	s_add_u32 s6, s6, s21
	s_addc_u32 s7, s7, 0
	v_pk_mul_f32 v[0:1], v[98:99], v[0:1] op_sel_hi:[0,1]
	v_pk_mul_f32 v[2:3], v[98:99], v[2:3] op_sel_hi:[0,1]
	v_pk_mul_f32 v[4:5], v[98:99], v[4:5] op_sel_hi:[0,1]
	v_pk_mul_f32 v[6:7], v[98:99], v[6:7] op_sel_hi:[0,1]
	v_pk_mul_f32 v[8:9], v[98:99], v[8:9] op_sel_hi:[0,1]
	v_pk_mul_f32 v[10:11], v[98:99], v[10:11] op_sel_hi:[0,1]
	v_pk_mul_f32 v[12:13], v[98:99], v[12:13] op_sel_hi:[0,1]
	v_pk_mul_f32 v[14:15], v[98:99], v[14:15] op_sel_hi:[0,1]
	v_pk_mul_f32 v[16:17], v[98:99], v[16:17] op_sel_hi:[0,1]
	v_pk_mul_f32 v[18:19], v[98:99], v[18:19] op_sel_hi:[0,1]
	v_pk_mul_f32 v[20:21], v[98:99], v[20:21] op_sel_hi:[0,1]
	v_pk_mul_f32 v[22:23], v[98:99], v[22:23] op_sel_hi:[0,1]
	v_pk_mul_f32 v[24:25], v[98:99], v[24:25] op_sel_hi:[0,1]
; __device__ __forceinline__ unsigned cvtpk(float lo, float hi) { f32x2_t v = {lo, hi}; bf16x2_t b = __builtin_convertvector(v, bf16x2_t); return __builtin_bit_cast(unsigned, b); }
; __global__ void __launch_bounds__(NTHREADS, 2) fwd_megakernel(Args args) {
;     ...
;         for (int j = 0; j < 8; ++j) { const int c = 4 * (lane + 64 * j); const f32x4 xv = __builtin_nontemporal_load((const f32x4*)(xr + c)); const v2u mv = *(const v2u*)(mr + c);
;             v[j] = xv * ALPHA + (f32x4){bflo(mv.x), bfhi(mv.x), bflo(mv.y), bfhi(mv.y)}; s += (v[j][0] + v[j][1]) + (v[j][2] + v[j][3]); }
;         const float mean = wave_sum(s) * (1.f / DM); float s2 = 0.f;
; #pragma unroll
;         for (int j = 0; j < 8; ++j) { v[j] = v[j] - mean; s2 += (v[j][0] * v[j][0] + v[j][1] * v[j][1]) + (v[j][2] * v[j][2] + v[j][3] * v[j][3]); }
;         const float rstd = 1.f / sqrtf(wave_sum(s2) * (1.f / DM) + LN_EPS);
; #pragma unroll
;         for (int j = 0; j < 8; ++j) { const int c = 4 * (lane + 64 * j); const f32x4 gg = *(const f32x4*)(ln1_g + c), bb = *(const f32x4*)(ln1_b + c);
;             const f32x4 o = v[j] * rstd * gg + bb; *(f32x4*)(row + c) = o;
;             v2u wv; wv.x = cvtpk(o[0], o[1]); wv.y = cvtpk(o[2], o[3]); *(v2u*)(HB + (size_t)m * DM + c) = wv; }
	v_pk_mul_f32 v[26:27], v[98:99], v[26:27] op_sel_hi:[0,1]
	v_pk_mul_f32 v[28:29], v[98:99], v[28:29] op_sel_hi:[0,1]
	v_pk_mul_f32 v[30:31], v[98:99], v[30:31] op_sel_hi:[0,1]
	v_pk_fma_f32 v[0:1], v[0:1], v[112:113], v[144:145]
	v_pk_fma_f32 v[2:3], v[2:3], v[114:115], v[146:147]
	v_pk_fma_f32 v[4:5], v[4:5], v[116:117], v[148:149]
	v_pk_fma_f32 v[6:7], v[6:7], v[118:119], v[150:151]
	v_pk_fma_f32 v[8:9], v[8:9], v[120:121], v[152:153]
	v_pk_fma_f32 v[10:11], v[10:11], v[122:123], v[154:155]
	v_pk_fma_f32 v[12:13], v[12:13], v[124:125], v[156:157]
	v_pk_fma_f32 v[14:15], v[14:15], v[126:127], v[158:159]
	v_pk_fma_f32 v[16:17], v[16:17], v[128:129], v[160:161]
	v_pk_fma_f32 v[18:19], v[18:19], v[130:131], v[162:163]
	v_pk_fma_f32 v[20:21], v[20:21], v[132:133], v[164:165]
	v_pk_fma_f32 v[22:23], v[22:23], v[134:135], v[166:167]
	v_pk_fma_f32 v[24:25], v[24:25], v[136:137], v[168:169]
	v_pk_fma_f32 v[26:27], v[26:27], v[138:139], v[170:171]
	v_pk_fma_f32 v[28:29], v[28:29], v[140:141], v[172:173]
	v_pk_fma_f32 v[30:31], v[30:31], v[142:143], v[174:175]
	v_cvt_pk_bf16_f32 v0, v0, v1
	v_cvt_pk_bf16_f32 v1, v2, v3
	v_cvt_pk_bf16_f32 v4, v4, v5
	v_cvt_pk_bf16_f32 v5, v6, v7
	v_cvt_pk_bf16_f32 v8, v8, v9
	v_cvt_pk_bf16_f32 v9, v10, v11
	v_cvt_pk_bf16_f32 v12, v12, v13
	v_cvt_pk_bf16_f32 v13, v14, v15
	v_cvt_pk_bf16_f32 v16, v16, v17
	v_cvt_pk_bf16_f32 v17, v18, v19
	v_cvt_pk_bf16_f32 v20, v20, v21
	v_cvt_pk_bf16_f32 v21, v22, v23
	v_cvt_pk_bf16_f32 v24, v24, v25
	v_cvt_pk_bf16_f32 v25, v26, v27
	v_cvt_pk_bf16_f32 v28, v28, v29
	v_cvt_pk_bf16_f32 v29, v30, v31
	global_store_dwordx2 v108, v[0:1], s[8:9]
	global_store_dwordx2 v108, v[4:5], s[8:9] offset:512
	global_store_dwordx2 v108, v[8:9], s[8:9] offset:1024
	global_store_dwordx2 v108, v[12:13], s[8:9] offset:1536
	global_store_dwordx2 v108, v[16:17], s[8:9] offset:2048
	global_store_dwordx2 v108, v[20:21], s[8:9] offset:2560
	global_store_dwordx2 v108, v[24:25], s[8:9] offset:3072
	global_store_dwordx2 v108, v[28:29], s[8:9] offset:3584
	s_add_u32 s8, s8, s21
	s_addc_u32 s9, s9, 0
	s_waitcnt vmcnt(8)
	v_lshlrev_b32_e32 v0, 16, v32
	v_and_b32_e32 v1, 0xffff0000, v32
	v_lshlrev_b32_e32 v2, 16, v33
	v_and_b32_e32 v3, 0xffff0000, v33
	v_lshlrev_b32_e32 v4, 16, v34
	v_and_b32_e32 v5, 0xffff0000, v34
	v_lshlrev_b32_e32 v6, 16, v35
	v_and_b32_e32 v7, 0xffff0000, v35
	v_lshlrev_b32_e32 v8, 16, v36
	v_and_b32_e32 v9, 0xffff0000, v36
	v_lshlrev_b32_e32 v10, 16, v37
	v_and_b32_e32 v11, 0xffff0000, v37
	v_lshlrev_b32_e32 v12, 16, v38
	v_and_b32_e32 v13, 0xffff0000, v38
	v_lshlrev_b32_e32 v14, 16, v39
	v_and_b32_e32 v15, 0xffff0000, v39
	v_lshlrev_b32_e32 v16, 16, v40
	v_and_b32_e32 v17, 0xffff0000, v40
	v_lshlrev_b32_e32 v18, 16, v41
	v_and_b32_e32 v19, 0xffff0000, v41
	v_lshlrev_b32_e32 v20, 16, v42
	v_and_b32_e32 v21, 0xffff0000, v42
	v_lshlrev_b32_e32 v22, 16, v43
	v_and_b32_e32 v23, 0xffff0000, v43
	v_lshlrev_b32_e32 v24, 16, v44
	v_and_b32_e32 v25, 0xffff0000, v44
	v_lshlrev_b32_e32 v26, 16, v45
	v_and_b32_e32 v27, 0xffff0000, v45
	v_lshlrev_b32_e32 v28, 16, v46
	v_and_b32_e32 v29, 0xffff0000, v46
	v_lshlrev_b32_e32 v30, 16, v47
	v_and_b32_e32 v31, 0xffff0000, v47
	v_pk_fma_f32 v[64:65], v[64:65], s[10:11], v[0:1] op_sel_hi:[1,0,1]
	v_pk_fma_f32 v[66:67], v[66:67], s[10:11], v[2:3] op_sel_hi:[1,0,1]
	v_pk_fma_f32 v[68:69], v[68:69], s[10:11], v[4:5] op_sel_hi:[1,0,1]
	v_pk_fma_f32 v[70:71], v[70:71], s[10:11], v[6:7] op_sel_hi:[1,0,1]
	v_pk_fma_f32 v[72:73], v[72:73], s[10:11], v[8:9] op_sel_hi:[1,0,1]
	v_pk_fma_f32 v[74:75], v[74:75], s[10:11], v[10:11] op_sel_hi:[1,0,1]
	v_pk_fma_f32 v[76:77], v[76:77], s[10:11], v[12:13] op_sel_hi:[1,0,1]
	v_pk_fma_f32 v[78:79], v[78:79], s[10:11], v[14:15] op_sel_hi:[1,0,1]
	v_pk_fma_f32 v[80:81], v[80:81], s[10:11], v[16:17] op_sel_hi:[1,0,1]
	v_pk_fma_f32 v[82:83], v[82:83], s[10:11], v[18:19] op_sel_hi:[1,0,1]
	v_pk_fma_f32 v[84:85], v[84:85], s[10:11], v[20:21] op_sel_hi:[1,0,1]
	v_pk_fma_f32 v[86:87], v[86:87], s[10:11], v[22:23] op_sel_hi:[1,0,1]
	v_pk_fma_f32 v[88:89], v[88:89], s[10:11], v[24:25] op_sel_hi:[1,0,1]
	v_pk_fma_f32 v[90:91], v[90:91], s[10:11], v[26:27] op_sel_hi:[1,0,1]
	v_pk_fma_f32 v[92:93], v[92:93], s[10:11], v[28:29] op_sel_hi:[1,0,1]
	v_pk_fma_f32 v[94:95], v[94:95], s[10:11], v[30:31] op_sel_hi:[1,0,1]
	v_pk_add_f32 v[0:1], v[64:65], v[66:67]
	v_pk_add_f32 v[2:3], v[68:69], v[70:71]
	v_pk_add_f32 v[4:5], v[72:73], v[74:75]
	v_pk_add_f32 v[6:7], v[76:77], v[78:79]
	v_pk_add_f32 v[8:9], v[80:81], v[82:83]
	v_pk_add_f32 v[10:11], v[84:85], v[86:87]
	v_pk_add_f32 v[12:13], v[88:89], v[90:91]
	v_pk_add_f32 v[14:15], v[92:93], v[94:95]
	v_pk_add_f32 v[16:17], v[0:1], v[2:3]
	v_pk_add_f32 v[18:19], v[4:5], v[6:7]
	v_pk_add_f32 v[20:21], v[8:9], v[10:11]
	v_pk_add_f32 v[22:23], v[12:13], v[14:15]
	v_pk_add_f32 v[0:1], v[16:17], v[18:19]
	v_pk_add_f32 v[2:3], v[20:21], v[22:23]
	s_nop 0
	v_pk_add_f32 v[0:1], v[0:1], v[2:3]
	s_nop 0
	v_add_f32_e32 v96, v0, v1
	ds_bpermute_b32 v97, v109, v96
	s_waitcnt lgkmcnt(0)
	v_add_f32_e32 v96, v96, v97
	ds_bpermute_b32 v97, v110, v96
	s_waitcnt lgkmcnt(0)
	v_add_f32_e32 v96, v96, v97
	ds_bpermute_b32 v97, v111, v96
	s_waitcnt lgkmcnt(0)
	v_add_f32_e32 v96, v96, v97
	ds_bpermute_b32 v97, v240, v96
	s_waitcnt lgkmcnt(0)
	v_add_f32_e32 v96, v96, v97
	ds_bpermute_b32 v97, v241, v96
	s_waitcnt lgkmcnt(0)
	v_add_f32_e32 v96, v96, v97
	ds_bpermute_b32 v97, v242, v96
	s_waitcnt lgkmcnt(0)
; __global__ void __launch_bounds__(NTHREADS, 2) fwd_megakernel(Args args) {
;     ...
;         float* row = HF + (size_t)m * DM; const float* xr = x + (size_t)m * DM; const bf16* mr = MIXB + (size_t)m * DM; f32x4 v[8]; float s = 0.f;
; #pragma unroll
;         for (int j = 0; j < 8; ++j) { const int c = 4 * (lane + 64 * j); const f32x4 xv = __builtin_nontemporal_load((const f32x4*)(xr + c)); const v2u mv = *(const v2u*)(mr + c);
;             v[j] = xv * ALPHA + (f32x4){bflo(mv.x), bfhi(mv.x), bflo(mv.y), bfhi(mv.y)}; s += (v[j][0] + v[j][1]) + (v[j][2] + v[j][3]); }
;         const float mean = wave_sum(s) * (1.f / DM); float s2 = 0.f;
; #pragma unroll
;         for (int j = 0; j < 8; ++j) { v[j] = v[j] - mean; s2 += (v[j][0] * v[j][0] + v[j][1] * v[j][1]) + (v[j][2] * v[j][2] + v[j][3] * v[j][3]); }
;         const float rstd = 1.f / sqrtf(wave_sum(s2) * (1.f / DM) + LN_EPS);
	v_add_f32_e32 v96, v96, v97
	v_mul_f32_e32 v96, 0xba000000, v96
	v_pk_add_f32 v[64:65], v[64:65], v[96:97] op_sel_hi:[1,0]
	v_pk_add_f32 v[66:67], v[66:67], v[96:97] op_sel_hi:[1,0]
	v_pk_add_f32 v[68:69], v[68:69], v[96:97] op_sel_hi:[1,0]
	v_pk_add_f32 v[70:71], v[70:71], v[96:97] op_sel_hi:[1,0]
	v_pk_add_f32 v[72:73], v[72:73], v[96:97] op_sel_hi:[1,0]
	v_pk_add_f32 v[74:75], v[74:75], v[96:97] op_sel_hi:[1,0]
	v_pk_add_f32 v[76:77], v[76:77], v[96:97] op_sel_hi:[1,0]
	v_pk_add_f32 v[78:79], v[78:79], v[96:97] op_sel_hi:[1,0]
	v_pk_add_f32 v[80:81], v[80:81], v[96:97] op_sel_hi:[1,0]
	v_pk_add_f32 v[82:83], v[82:83], v[96:97] op_sel_hi:[1,0]
	v_pk_add_f32 v[84:85], v[84:85], v[96:97] op_sel_hi:[1,0]
	v_pk_add_f32 v[86:87], v[86:87], v[96:97] op_sel_hi:[1,0]
	v_pk_add_f32 v[88:89], v[88:89], v[96:97] op_sel_hi:[1,0]
	v_pk_add_f32 v[90:91], v[90:91], v[96:97] op_sel_hi:[1,0]
	v_pk_add_f32 v[92:93], v[92:93], v[96:97] op_sel_hi:[1,0]
	v_pk_add_f32 v[94:95], v[94:95], v[96:97] op_sel_hi:[1,0]
	v_pk_mul_f32 v[0:1], v[64:65], v[64:65]
	v_pk_mul_f32 v[2:3], v[68:69], v[68:69]
	v_pk_mul_f32 v[4:5], v[72:73], v[72:73]
	v_pk_mul_f32 v[6:7], v[76:77], v[76:77]
	v_pk_fma_f32 v[0:1], v[66:67], v[66:67], v[0:1]
	v_pk_fma_f32 v[2:3], v[70:71], v[70:71], v[2:3]
	v_pk_fma_f32 v[4:5], v[74:75], v[74:75], v[4:5]
	v_pk_fma_f32 v[6:7], v[78:79], v[78:79], v[6:7]
	v_pk_fma_f32 v[0:1], v[80:81], v[80:81], v[0:1]
	v_pk_fma_f32 v[2:3], v[84:85], v[84:85], v[2:3]
	v_pk_fma_f32 v[4:5], v[88:89], v[88:89], v[4:5]
	v_pk_fma_f32 v[6:7], v[92:93], v[92:93], v[6:7]
	v_pk_fma_f32 v[0:1], v[82:83], v[82:83], v[0:1]
	v_pk_fma_f32 v[2:3], v[86:87], v[86:87], v[2:3]
	v_pk_fma_f32 v[4:5], v[90:91], v[90:91], v[4:5]
	v_pk_fma_f32 v[6:7], v[94:95], v[94:95], v[6:7]
	v_pk_add_f32 v[0:1], v[0:1], v[2:3]
	v_pk_add_f32 v[4:5], v[4:5], v[6:7]
	s_nop 0
	v_pk_add_f32 v[0:1], v[0:1], v[4:5]
	s_nop 0
	v_add_f32_e32 v96, v0, v1
	ds_bpermute_b32 v97, v109, v96
	s_waitcnt lgkmcnt(0)
	v_add_f32_e32 v96, v96, v97
	ds_bpermute_b32 v97, v110, v96
	s_waitcnt lgkmcnt(0)
	v_add_f32_e32 v96, v96, v97
	ds_bpermute_b32 v97, v111, v96
	s_waitcnt lgkmcnt(0)
	v_add_f32_e32 v96, v96, v97
	ds_bpermute_b32 v97, v240, v96
	s_waitcnt lgkmcnt(0)
	v_add_f32_e32 v96, v96, v97
	ds_bpermute_b32 v97, v241, v96
	s_waitcnt lgkmcnt(0)
	v_add_f32_e32 v96, v96, v97
	ds_bpermute_b32 v97, v242, v96
	s_waitcnt lgkmcnt(0)
	v_add_f32_e32 v96, v96, v97
	v_fmamk_f32 v98, v96, 0x3a000000, v105
	v_mul_f32_e32 v99, 0x4f800000, v98
	v_cmp_gt_f32_e32 vcc, s1, v98
	s_nop 1
	v_cndmask_b32_e32 v98, v98, v99, vcc
	v_sqrt_f32_e32 v99, v98
	s_nop 0
	v_add_u32_e32 v100, -1, v99
	v_add_u32_e32 v101, 1, v99
	v_fma_f32 v102, -v100, v99, v98
	v_fma_f32 v103, -v101, v99, v98
	v_cmp_ge_f32_e64 s[22:23], 0, v102
	s_nop 1
	v_cndmask_b32_e64 v99, v99, v100, s[22:23]
	v_cmp_lt_f32_e64 s[22:23], 0, v103
	s_nop 1
	v_cndmask_b32_e64 v99, v99, v101, s[22:23]
	v_mul_f32_e32 v100, 0x37800000, v99
	v_cndmask_b32_e32 v99, v99, v100, vcc
	v_cmp_class_f32_e32 vcc, v98, v104
	s_nop 1
	v_cndmask_b32_e32 v98, v99, v98, vcc
	v_div_scale_f32 v99, s[22:23], v98, v98, 1.0
	v_rcp_f32_e32 v101, v99
	v_div_scale_f32 v100, vcc, 1.0, v98, 1.0
	v_fma_f32 v102, -v99, v101, 1.0
	v_fmac_f32_e32 v101, v102, v101
	v_mul_f32_e32 v102, v100, v101
	v_fma_f32 v103, -v99, v102, v100
	v_fmac_f32_e32 v102, v103, v101
	v_fma_f32 v99, -v99, v102, v100
	v_div_fmas_f32 v99, v99, v101, v102
	v_div_fixup_f32 v98, v99, v98, 1.0
	s_add_i32 s0, s0, s28
	s_cmp_lt_i32 s0, 0x8000
	s_cbranch_scc0 .Lp5r_last
	global_load_dwordx4 v[0:3], v106, s[4:5] nt
	global_load_dwordx4 v[4:7], v106, s[4:5] offset:1024 nt
	global_load_dwordx4 v[8:11], v106, s[4:5] offset:2048 nt
	global_load_dwordx4 v[12:15], v106, s[4:5] offset:3072 nt
	global_load_dwordx4 v[16:19], v107, s[4:5] nt
	global_load_dwordx4 v[20:23], v107, s[4:5] offset:1024 nt
	global_load_dwordx4 v[24:27], v107, s[4:5] offset:2048 nt
	global_load_dwordx4 v[28:31], v107, s[4:5] offset:3072 nt
	global_load_dwordx2 v[32:33], v108, s[6:7]
	global_load_dwordx2 v[34:35], v108, s[6:7] offset:512
	global_load_dwordx2 v[36:37], v108, s[6:7] offset:1024
	global_load_dwordx2 v[38:39], v108, s[6:7] offset:1536
	global_load_dwordx2 v[40:41], v108, s[6:7] offset:2048
	global_load_dwordx2 v[42:43], v108, s[6:7] offset:2560
	global_load_dwordx2 v[44:45], v108, s[6:7] offset:3072
	global_load_dwordx2 v[46:47], v108, s[6:7] offset:3584
	s_add_u32 s4, s4, s20
	s_addc_u32 s5, s5, 0
	s_add_u32 s6, s6, s21
	s_addc_u32 s7, s7, 0
; __device__ __forceinline__ unsigned cvtpk(float lo, float hi) { f32x2_t v = {lo, hi}; bf16x2_t b = __builtin_convertvector(v, bf16x2_t); return __builtin_bit_cast(unsigned, b); }
; __global__ void __launch_bounds__(NTHREADS, 2) fwd_megakernel(Args args) {
;     ...
;         for (int j = 0; j < 8; ++j) { const int c = 4 * (lane + 64 * j); const f32x4 gg = *(const f32x4*)(ln1_g + c), bb = *(const f32x4*)(ln1_b + c);
;             const f32x4 o = v[j] * rstd * gg + bb; *(f32x4*)(row + c) = o;
;             v2u wv; wv.x = cvtpk(o[0], o[1]); wv.y = cvtpk(o[2], o[3]); *(v2u*)(HB + (size_t)m * DM + c) = wv; }
.Lp5r_last:
	v_pk_mul_f32 v[64:65], v[98:99], v[64:65] op_sel_hi:[0,1]
	v_pk_mul_f32 v[66:67], v[98:99], v[66:67] op_sel_hi:[0,1]
	v_pk_mul_f32 v[68:69], v[98:99], v[68:69] op_sel_hi:[0,1]
	v_pk_mul_f32 v[70:71], v[98:99], v[70:71] op_sel_hi:[0,1]
	v_pk_mul_f32 v[72:73], v[98:99], v[72:73] op_sel_hi:[0,1]
	v_pk_mul_f32 v[74:75], v[98:99], v[74:75] op_sel_hi:[0,1]
	v_pk_mul_f32 v[76:77], v[98:99], v[76:77] op_sel_hi:[0,1]
	v_pk_mul_f32 v[78:79], v[98:99], v[78:79] op_sel_hi:[0,1]
	v_pk_mul_f32 v[80:81], v[98:99], v[80:81] op_sel_hi:[0,1]
	v_pk_mul_f32 v[82:83], v[98:99], v[82:83] op_sel_hi:[0,1]
	v_pk_mul_f32 v[84:85], v[98:99], v[84:85] op_sel_hi:[0,1]
	v_pk_mul_f32 v[86:87], v[98:99], v[86:87] op_sel_hi:[0,1]
	v_pk_mul_f32 v[88:89], v[98:99], v[88:89] op_sel_hi:[0,1]
	v_pk_mul_f32 v[90:91], v[98:99], v[90:91] op_sel_hi:[0,1]
	v_pk_mul_f32 v[92:93], v[98:99], v[92:93] op_sel_hi:[0,1]
	v_pk_mul_f32 v[94:95], v[98:99], v[94:95] op_sel_hi:[0,1]
	v_pk_fma_f32 v[64:65], v[64:65], v[112:113], v[144:145]
	v_pk_fma_f32 v[66:67], v[66:67], v[114:115], v[146:147]
	v_pk_fma_f32 v[68:69], v[68:69], v[116:117], v[148:149]
	v_pk_fma_f32 v[70:71], v[70:71], v[118:119], v[150:151]
	v_pk_fma_f32 v[72:73], v[72:73], v[120:121], v[152:153]
	v_pk_fma_f32 v[74:75], v[74:75], v[122:123], v[154:155]
	v_pk_fma_f32 v[76:77], v[76:77], v[124:125], v[156:157]
	v_pk_fma_f32 v[78:79], v[78:79], v[126:127], v[158:159]
	v_pk_fma_f32 v[80:81], v[80:81], v[128:129], v[160:161]
	v_pk_fma_f32 v[82:83], v[82:83], v[130:131], v[162:163]
	v_pk_fma_f32 v[84:85], v[84:85], v[132:133], v[164:165]
	v_pk_fma_f32 v[86:87], v[86:87], v[134:135], v[166:167]
	v_pk_fma_f32 v[88:89], v[88:89], v[136:137], v[168:169]
	v_pk_fma_f32 v[90:91], v[90:91], v[138:139], v[170:171]
	v_pk_fma_f32 v[92:93], v[92:93], v[140:141], v[172:173]
	v_pk_fma_f32 v[94:95], v[94:95], v[142:143], v[174:175]
	v_cvt_pk_bf16_f32 v64, v64, v65
	v_cvt_pk_bf16_f32 v65, v66, v67
	v_cvt_pk_bf16_f32 v68, v68, v69
	v_cvt_pk_bf16_f32 v69, v70, v71
	v_cvt_pk_bf16_f32 v72, v72, v73
	v_cvt_pk_bf16_f32 v73, v74, v75
	v_cvt_pk_bf16_f32 v76, v76, v77
	v_cvt_pk_bf16_f32 v77, v78, v79
	v_cvt_pk_bf16_f32 v80, v80, v81
	v_cvt_pk_bf16_f32 v81, v82, v83
	v_cvt_pk_bf16_f32 v84, v84, v85
	v_cvt_pk_bf16_f32 v85, v86, v87
	v_cvt_pk_bf16_f32 v88, v88, v89
	v_cvt_pk_bf16_f32 v89, v90, v91
	v_cvt_pk_bf16_f32 v92, v92, v93
	v_cvt_pk_bf16_f32 v93, v94, v95
	global_store_dwordx2 v108, v[64:65], s[8:9]
	global_store_dwordx2 v108, v[68:69], s[8:9] offset:512
	global_store_dwordx2 v108, v[72:73], s[8:9] offset:1024
	global_store_dwordx2 v108, v[76:77], s[8:9] offset:1536
	global_store_dwordx2 v108, v[80:81], s[8:9] offset:2048
	global_store_dwordx2 v108, v[84:85], s[8:9] offset:2560
	global_store_dwordx2 v108, v[88:89], s[8:9] offset:3072
	global_store_dwordx2 v108, v[92:93], s[8:9] offset:3584
	s_add_u32 s8, s8, s21
	s_addc_u32 s9, s9, 0
	s_cmp_lt_i32 s0, 0x8000
	s_cbranch_scc1 .Lp5r_loop
